# attention pair loop: shorter interval header, producer requests first V transpose-read group at interval head
# baseline (speedup 1.0000x reference)
; #define SBAR() __builtin_amdgcn_sched_barrier(0)
; #define KLOAD(k0) do { ks0 = *reinterpret_cast<const bf16x8*>(&Kh[(long)((k0) + sr) * LDK + sc]); ks1 = *reinterpret_cast<const bf16x8*>(&Kh[(long)((k0) + 32 + sr) * LDK + sc]); } while (0)
; #define KWRITE(b) do { const int kc = sc * 2; *(bf16x8*)(K_lds + (b) * 16384 + KSWZ(sr, kc)) = ks0; *(bf16x8*)(K_lds + (b) * 16384 + KSWZ(32 + sr, kc)) = ks1; } while (0)
; __device__ __forceinline__ void partialSM(f32x16& p0, f32x16& p1, float& m_reg, float& mn, float& alpha) {
;   constexpr float C = SCALE * 1.4426950408889634f;
;   float pmax = p0[0]; for (int r = 1; r < 16; ++r) pmax = fmaxf(pmax, p0[r]); for (int r = 0; r < 16; ++r) pmax = fmaxf(pmax, p1[r]);
;   { auto rr = __builtin_amdgcn_permlane32_swap(__float_as_uint(pmax), __float_as_uint(pmax), false, false);
;     pmax = fmaxf(__uint_as_float(rr[0]), __uint_as_float(rr[1])); }
;   if (__builtin_expect(__all(pmax - m_reg <= THR / SCALE), 1)) { mn = m_reg; alpha = 1.f; }
;   else { mn = fmaxf(m_reg, pmax); alpha = __builtin_amdgcn_exp2f((m_reg - mn) * C); m_reg = mn; }
; template <int LDQ, int LDK, int LDO>
; __device__ __forceinline__ void attn_pair_body(const bf16* __restrict__ Qb, const bf16* __restrict__ Kh, const bf16* __restrict__ Vh, float* __restrict__ Ob, int NT, char* lds, int tid_in) {
;     ...
;   for (int j = 0; j <= NT; ++j) {
;     const int b = j & 1, pb = b ^ 1;
;     const bool prod = (j < NT) && (b == vhw);
;     if (prod) __builtin_amdgcn_s_setprio(2); else __builtin_amdgcn_s_setprio(0);
;     const bool flp = (j >= 1) && (__builtin_amdgcn_readfirstlane((int)FLp[pb]) != 0);
;     const float alp_v = ALp[pb * 32 + r32], m_v = Mp[r32];
;     const bf16x8 a0 = *reinterpret_cast<const bf16x8*>(Pp + pb * 4096 + 0 * 1024 + lane * 16), a1 = *reinterpret_cast<const bf16x8*>(Pp + pb * 4096 + 1 * 1024 + lane * 16);
;     const bf16x8 a2 = *reinterpret_cast<const bf16x8*>(Pp + pb * 4096 + 2 * 1024 + lane * 16), a3 = *reinterpret_cast<const bf16x8*>(Pp + pb * 4096 + 3 * 1024 + lane * 16);
;     SBAR();
;     KWRITE(b);
;     VWRITE(b);
;     { const int tk = j + 3 < NT ? j + 3 : NT - 1, tv = j + 1 < NT ? j + 1 : NT - 1; KLOAD(tk * KVBLK); VLOAD(tv * KVBLK); }
;     SBAR();
;     if (prod) {
;       if (flp) l_reg *= alp_v;
;       if (j >= 1) m_reg = m_v;
;       float mn, al; bf16x8 pa0, pa1, pa2, pa3;
;       partialSM(p0, p1, m_reg, mn, al);
.LBB0_1017:
	s_add_i32 s15, s11, -1
	s_and_b32 s28, s15, 1
	s_xor_b32 s21, s28, 1
	s_cmp_lg_u32 s15, 0
	s_cselect_b64 s[56:57], -1, 0
	s_cselect_b64 s[44:45], 0, -1
	s_cmp_eq_u32 s28, s8
	s_cselect_b64 s[52:53], -1, 0
	s_cmp_lt_i32 s15, s4
	s_cselect_b64 s[42:43], -1, 0
	s_and_b64 s[42:43], s[42:43], s[52:53]
	s_cbranch_scc0 .Lpa_np
	s_setprio 2
	s_mov_b64 s[42:43], 0
	s_branch .Lpa_hd
.Lpa_np:
	s_setprio 0
	s_mov_b64 s[42:43], -1
.Lpa_hd:
	s_lshl_b32 s29, s21, 2
	s_add_i32 s29, s10, s29
	v_mov_b32_e32 v210, s29
	ds_read_b32 v210, v210
.LBB0_1023:
	v_lshl_add_u32 v156, s21, 7, v214
	v_lshl_add_u32 v157, s21, 12, v216
	ds_read_b32 v219, v156
	ds_read_b128 v[168:171], v157
	ds_read_b32 v220, v212
	ds_read_b128 v[164:167], v157 offset:1024
	ds_read_b128 v[160:163], v157 offset:2048
	ds_read_b128 v[156:159], v157 offset:3072
	s_and_b64 vcc, exec, s[42:43]
	s_cbranch_vccnz .Lpa_cons
	v_lshl_add_u32 v176, s21, 15, v211
	ds_read_b64_tr_b16 v[132:133], v176 offset:0
	ds_read_b64_tr_b16 v[134:135], v176 offset:0x800
	ds_read_b64_tr_b16 v[136:137], v176 offset:0x1000
	ds_read_b64_tr_b16 v[138:139], v176 offset:0x1800
	ds_read_b64_tr_b16 v[140:141], v176 offset:0x2000
	ds_read_b64_tr_b16 v[142:143], v176 offset:0x2800
	ds_read_b64_tr_b16 v[144:145], v176 offset:0x3000
	ds_read_b64_tr_b16 v[146:147], v176 offset:0x3800
	s_lshl_b32 s29, s28, 14
	s_add_i32 s29, s29, s32
	s_lshl_b32 s28, s28, 15
	s_add_i32 s28, s28, s58
	s_add_i32 s46, s11, 1
	s_add_i32 s47, s11, -1
	s_min_i32 s46, s46, s12
	s_min_i32 s47, s47, s12
	s_mul_i32 s46, s46, 0x90000
	s_mul_i32 s47, s47, 0x90000
	s_add_u32 s74, s60, s46
	s_addc_u32 s75, s61, 0
	s_add_u32 s92, s68, s47
	s_addc_u32 s93, s69, 0
	s_mov_b32 m0, s29
	s_add_i32 s29, s29, 0x400
	global_load_lds_dwordx4 v172, s[74:75]
	s_mov_b32 m0, s29
	s_nop 0
	global_load_lds_dwordx4 v173, s[74:75]
	s_mov_b32 m0, s28
	s_add_i32 s28, s28, 0x400
	global_load_lds_dwordx4 v174, s[92:93]
	s_mov_b32 m0, s28
	s_add_u32 s92, s92, 0x80
	s_addc_u32 s93, s93, 0
	global_load_lds_dwordx4 v174, s[92:93]
	s_add_i32 s28, s28, 0x400
	s_mov_b32 m0, s28
	s_add_u32 s92, s92, 0x8f80
	s_addc_u32 s93, s93, 0
	global_load_lds_dwordx4 v174, s[92:93]
	s_add_i32 s28, s28, 0x400
	s_mov_b32 m0, s28
	s_add_u32 s92, s92, 0x80
	s_addc_u32 s93, s93, 0
	global_load_lds_dwordx4 v174, s[92:93]
	v_max_f32_e32 v176, v85, v85
	v_max_f32_e32 v177, v84, v84
	v_max_f32_e32 v176, v177, v176
	v_max3_f32 v176, v176, v86, v87
	v_max3_f32 v176, v176, v88, v89
	v_max3_f32 v176, v176, v90, v91
	v_max3_f32 v176, v176, v92, v93
	v_max3_f32 v176, v176, v94, v95
	v_max3_f32 v176, v176, v96, v97
	v_max3_f32 v176, v176, v98, v99
	v_max3_f32 v176, v176, v68, v69
	v_max3_f32 v176, v176, v70, v71
	v_max3_f32 v176, v176, v72, v73
	v_max3_f32 v176, v176, v74, v75
	v_max3_f32 v176, v176, v76, v77
	v_max3_f32 v176, v176, v78, v79
	v_max3_f32 v176, v176, v80, v81
	v_max3_f32 v176, v176, v82, v83
	v_mov_b32_e32 v177, v176
	s_nop 1
	v_permlane32_swap_b32_e32 v176, v177
	v_max_f32_e32 v177, v177, v177
	v_max_f32_e32 v176, v176, v176
	s_waitcnt lgkmcnt(11)
	v_readfirstlane_b32 s29, v210
	s_cmp_lg_u32 s29, 0
	s_cselect_b64 s[62:63], -1, 0
	s_and_b64 s[62:63], s[62:63], s[56:57]
	v_cndmask_b32_e64 v217, v220, v217, s[44:45]
	v_max_f32_e32 v221, v176, v177
	v_sub_f32_e32 v176, v221, v217
	v_cmp_ge_f32_e32 vcc, s27, v176
	s_cmp_eq_u64 vcc, exec
	v_mov_b32_e32 v220, 1.0
	s_cbranch_scc0 .LBB0_1036

; #define SBAR() __builtin_amdgcn_sched_barrier(0)
; #define TRD(Lb, Hb, D0) Lb[0] = tr_read<v_rd_off(D0, 0, 0)>(vb); Hb[0] = tr_read<v_rd_off(D0, 0, 1)>(vb); Lb[1] = tr_read<v_rd_off(D0, 1, 0)>(vb); Hb[1] = tr_read<v_rd_off(D0, 1, 1)>(vb); \
;     Lb[2] = tr_read<v_rd_off(D0, 2, 0)>(vb); Hb[2] = tr_read<v_rd_off(D0, 2, 1)>(vb); Lb[3] = tr_read<v_rd_off(D0, 3, 0)>(vb); Hb[3] = tr_read<v_rd_off(D0, 3, 1)>(vb);
; #define MM(D0, Lb, Hb) o[D0] = __builtin_amdgcn_mfma_f32_32x32x16_bf16(pa0, PK(Lb[0], Hb[0]), o[D0], 0, 0, 0); o[D0] = __builtin_amdgcn_mfma_f32_32x32x16_bf16(pa1, PK(Lb[1], Hb[1]), o[D0], 0, 0, 0); \
;     o[D0] = __builtin_amdgcn_mfma_f32_32x32x16_bf16(pa2, PK(Lb[2], Hb[2]), o[D0], 0, 0, 0); o[D0] = __builtin_amdgcn_mfma_f32_32x32x16_bf16(pa3, PK(Lb[3], Hb[3]), o[D0], 0, 0, 0);
; __device__ __forceinline__ void pv_batched(f32x16* o, int vb, bf16x8 pa0, bf16x8 pa1, bf16x8 pa2, bf16x8 pa3) {
;   s16x4 L0[4], H0[4], L1[4], H1[4];
;     ...
;   TRD(L0, H0, 0) SBAR(); TRD(L1, H1, 1) SBAR();
;   asm volatile("s_waitcnt lgkmcnt(8)" ::: "memory"); SBAR();
;   MM(0, L0, H0) SBAR();
;   TRD(L0, H0, 2) SBAR();
;   asm volatile("s_waitcnt lgkmcnt(8)" ::: "memory"); SBAR();
;   MM(1, L1, H1) SBAR();
;   TRD(L1, H1, 3) SBAR();
;   asm volatile("s_waitcnt lgkmcnt(8)" ::: "memory"); SBAR();
;   MM(2, L0, H0) SBAR();
;   asm volatile("s_waitcnt lgkmcnt(0)" ::: "memory"); SBAR();
;   MM(3, L1, H1) SBAR();
.LBB0_1033:
	v_lshl_add_u32 v219, s21, 15, v211
	ds_read_b64_tr_b16 v[242:243], v219 offset:0x200
	ds_read_b64_tr_b16 v[244:245], v219 offset:0xa00
	ds_read_b64_tr_b16 v[246:247], v219 offset:0x1200
	ds_read_b64_tr_b16 v[248:249], v219 offset:0x1a00
	ds_read_b64_tr_b16 v[176:177], v219 offset:0x2200
	ds_read_b64_tr_b16 v[178:179], v219 offset:0x2a00
	ds_read_b64_tr_b16 v[228:229], v219 offset:0x3200
	ds_read_b64_tr_b16 v[230:231], v219 offset:0x3a00
	s_waitcnt lgkmcnt(8)
	s_nop 0
	v_mfma_f32_32x32x16_bf16 v[4:19], v[168:171], v[132:135], v[4:19]
	s_waitcnt lgkmcnt(8)
	v_mfma_f32_32x32x16_bf16 v[4:19], v[164:167], v[136:139], v[4:19]
	s_waitcnt lgkmcnt(7)
	v_mfma_f32_32x32x16_bf16 v[4:19], v[160:163], v[140:143], v[4:19]
	s_waitcnt lgkmcnt(6)
	v_mfma_f32_32x32x16_bf16 v[4:19], v[156:159], v[144:147], v[4:19]
	ds_read_b64_tr_b16 v[220:221], v219 offset:0x400
	ds_read_b64_tr_b16 v[222:223], v219 offset:0xc00
	ds_read_b64_tr_b16 v[224:225], v219 offset:0x1400
	ds_read_b64_tr_b16 v[226:227], v219 offset:0x1c00
	ds_read_b64_tr_b16 v[232:233], v219 offset:0x2400
	ds_read_b64_tr_b16 v[234:235], v219 offset:0x2c00
	ds_read_b64_tr_b16 v[236:237], v219 offset:0x3400
	ds_read_b64_tr_b16 v[238:239], v219 offset:0x3c00
	s_waitcnt lgkmcnt(8)
	v_mfma_f32_32x32x16_bf16 v[52:67], v[168:171], v[242:245], v[52:67]
	v_mfma_f32_32x32x16_bf16 v[52:67], v[164:167], v[246:249], v[52:67]
	v_mfma_f32_32x32x16_bf16 v[52:67], v[160:163], v[176:179], v[52:67]
	v_mfma_f32_32x32x16_bf16 v[52:67], v[156:159], v[228:231], v[52:67]
	ds_read_b64_tr_b16 v[176:177], v219 offset:0x600
	ds_read_b64_tr_b16 v[178:179], v219 offset:0xe00
	ds_read_b64_tr_b16 v[228:229], v219 offset:0x1600
	ds_read_b64_tr_b16 v[230:231], v219 offset:0x1e00
	ds_read_b64_tr_b16 v[240:241], v219 offset:0x2600
	ds_read_b64_tr_b16 v[242:243], v219 offset:0x2e00
	ds_read_b64_tr_b16 v[244:245], v219 offset:0x3600
	ds_read_b64_tr_b16 v[246:247], v219 offset:0x3e00
	s_waitcnt lgkmcnt(8)
	v_mfma_f32_32x32x16_bf16 v[36:51], v[168:171], v[220:223], v[36:51]
	v_mfma_f32_32x32x16_bf16 v[36:51], v[164:167], v[224:227], v[36:51]
	v_mfma_f32_32x32x16_bf16 v[36:51], v[160:163], v[232:235], v[36:51]
	v_mfma_f32_32x32x16_bf16 v[36:51], v[156:159], v[236:239], v[36:51]
	s_waitcnt lgkmcnt(0)
	v_mfma_f32_32x32x16_bf16 v[20:35], v[168:171], v[176:179], v[20:35]
	v_mfma_f32_32x32x16_bf16 v[20:35], v[164:167], v[228:231], v[20:35]
	v_mfma_f32_32x32x16_bf16 v[20:35], v[160:163], v[240:243], v[20:35]
	v_mfma_f32_32x32x16_bf16 v[20:35], v[156:159], v[244:247], v[20:35]
